# LN loops (P0 input LN, P5 LN1): gamma/beta loads hoisted out of the row loop + next-row L2 prefetch loads kept in flight under counted vmcnt
# speedup vs baseline: 1.1667x; 1.0052x over previous
.LBB0_101:
	s_or_b64 exec, exec, s[4:5]
	s_movk_i32 s30, 0x4100
	v_cndmask_b32_e64 v2, 0, 1, s[0:1]
	v_cmp_gt_i32_e32 vcc, s30, v14
	s_and_saveexec_b64 s[26:27], vcc
	s_cbranch_execz .LBB0_128
	v_mbcnt_lo_u32_b32 v3, -1, 0
	v_mbcnt_hi_u32_b32 v3, -1, v3
	v_and_b32_e32 v5, 64, v3
	v_add_u32_e32 v5, 64, v5
	v_xor_b32_e32 v6, 1, v3
	v_cmp_lt_i32_e32 vcc, v6, v5
	v_mov_b32_e32 v37, 0
	v_readlane_b32 s0, v250, 0
	v_cndmask_b32_e32 v6, v3, v6, vcc
	v_lshlrev_b32_e32 v62, 2, v6
	v_xor_b32_e32 v6, 2, v3
	v_cmp_lt_i32_e32 vcc, v6, v5
	v_lshlrev_b32_e32 v4, 2, v1
	v_lshlrev_b32_e32 v36, 4, v1
	v_cndmask_b32_e32 v6, v3, v6, vcc
	v_lshlrev_b32_e32 v63, 2, v6
	v_xor_b32_e32 v6, 4, v3
	v_cmp_lt_i32_e32 vcc, v6, v5
	v_mov_b32_e32 v1, v37
	s_lshl_b32 s31, s0, 3
	v_cndmask_b32_e32 v6, v3, v6, vcc
	v_lshlrev_b32_e32 v64, 2, v6
	v_xor_b32_e32 v6, 8, v3
	v_cmp_lt_i32_e32 vcc, v6, v5
	s_lshl_b32 s0, s28, 3
	v_lshl_add_u64 v[42:43], s[36:37], 0, v[0:1]
	v_cndmask_b32_e32 v6, v3, v6, vcc
	v_lshlrev_b32_e32 v65, 2, v6
	v_xor_b32_e32 v6, 16, v3
	v_cmp_lt_i32_e32 vcc, v6, v5
	v_subrev_u32_e32 v68, s0, v9
	s_lshl_b32 s0, s94, 3
	v_cndmask_b32_e32 v6, v3, v6, vcc
	v_lshlrev_b32_e32 v66, 2, v6
	v_xor_b32_e32 v6, 32, v3
	v_cmp_lt_i32_e32 vcc, v6, v5
	v_lshlrev_b32_e32 v0, 3, v2
	v_add_u32_e32 v0, s0, v0
	v_cndmask_b32_e32 v3, v3, v6, vcc
	s_lshl_b32 s0, s28, 4
	v_lshlrev_b32_e32 v67, 2, v3
	v_lshl_add_u64 v[38:39], s[56:57], 0, v[36:37]
	v_lshl_add_u64 v[40:41], s[58:59], 0, v[36:37]
	s_lshl_b32 s34, s29, 4
	v_subrev_u32_e32 v69, s0, v9
	v_add_u32_e32 v70, s31, v0
	s_mov_b64 s[28:29], 0
	s_movk_i32 s35, 0x407f
	s_mov_b32 s38, 0xfe03f81
	v_lshlrev_b32_e32 v36, 2, v4
	v_mov_b32_e32 v71, 0x3727c5ac
	s_mov_b32 s39, 0xf800000
	v_mov_b32_e32 v72, 0x260
	v_readlane_b32 s1, v250, 1
	global_load_dwordx4 v[84:87], v[38:39], off
	global_load_dwordx4 v[88:91], v[40:41], off
	global_load_dwordx4 v[92:95], v[38:39], off offset:1024
	global_load_dwordx4 v[96:99], v[40:41], off offset:1024
	global_load_dwordx4 v[100:103], v[38:39], off offset:2048
	global_load_dwordx4 v[104:107], v[40:41], off offset:2048
	global_load_dwordx4 v[108:111], v[38:39], off offset:3072
	global_load_dwordx4 v[112:115], v[40:41], off offset:3072
	s_waitcnt vmcnt(0)
	s_branch .LBB0_104

.LBB0_120:
	s_or_b64 exec, exec, s[0:1]
	v_lshlrev_b64 v[0:1], 12, v[0:1]
	v_lshl_add_u64 v[0:1], v[2:3], 0, v[0:1]
	v_lshl_add_u64 v[0:1], v[0:1], 0, v[36:37]
	global_load_dwordx4 v[28:31], v[0:1], off
	v_lshlrev_b64 v[2:3], 12, v[4:5]
	v_lshl_add_u64 v[2:3], v[6:7], 0, v[2:3]
	v_lshl_add_u64 v[2:3], v[2:3], 0, v[36:37]
	global_load_dwordx4 v[24:27], v[2:3], off
	global_load_dwordx4 v[20:23], v[0:1], off offset:1024
	global_load_dwordx4 v[16:19], v[2:3], off offset:1024
	global_load_dwordx4 v[12:15], v[0:1], off offset:2048
	global_load_dwordx4 v[8:11], v[2:3], off offset:2048
	global_load_dwordx4 v[4:7], v[0:1], off offset:3072
	s_nop 0
	global_load_dwordx4 v[0:3], v[2:3], off offset:3072
	v_add_u32_e32 v116, s34, v44
	v_mul_hi_i32 v117, v116, s38
	v_lshrrev_b32_e32 v118, 31, v117
	v_ashrrev_i32_e32 v117, 7, v117
	v_add_u32_e32 v117, v117, v118
	v_mul_i32_i24_e32 v118, 0xfffff7f0, v117
	v_add_u32_e32 v118, v118, v116
	v_lshl_add_u32 v119, v117, 11, v118
	v_add_u32_e32 v119, -16, v119
	v_cmp_ge_i32_e64 s[6:7], s35, v116
	v_cmp_lt_i32_e32 vcc, 15, v118
	s_and_b64 vcc, vcc, s[6:7]
	s_nop 1
	v_cndmask_b32_e32 v119, 0, v119, vcc
	v_lshl_add_u32 v120, v119, 12, v36
	v_add_u32_e32 v121, s34, v46
	v_mul_hi_i32 v122, v121, s38
	v_lshrrev_b32_e32 v123, 31, v122
	v_ashrrev_i32_e32 v122, 7, v122
	v_add_u32_e32 v122, v122, v123
	v_mul_i32_i24_e32 v123, 0xfffff7f0, v122
	v_add_u32_e32 v123, v123, v121
	v_lshl_add_u32 v124, v122, 11, v123
	v_add_u32_e32 v124, -16, v124
	v_cmp_ge_i32_e64 s[6:7], s35, v121
	v_cmp_lt_i32_e32 vcc, 15, v123
	s_and_b64 vcc, vcc, s[6:7]
	s_nop 1
	v_cndmask_b32_e32 v124, 0, v124, vcc
	v_lshl_add_u32 v125, v124, 12, v36
	global_load_dwordx4 v[128:131], v120, s[72:73]
	global_load_dwordx4 v[128:131], v120, s[72:73] offset:1024
	global_load_dwordx4 v[128:131], v120, s[72:73] offset:2048
	global_load_dwordx4 v[128:131], v120, s[72:73] offset:3072
	global_load_dwordx4 v[128:131], v125, s[72:73]
	global_load_dwordx4 v[128:131], v125, s[72:73] offset:1024
	global_load_dwordx4 v[128:131], v125, s[72:73] offset:2048
	global_load_dwordx4 v[128:131], v125, s[72:73] offset:3072
	s_waitcnt vmcnt(14)
	v_mov_b32_e32 v48, v25
	v_mov_b32_e32 v49, v26
	v_mov_b32_e32 v32, v29
	v_mov_b32_e32 v33, v30
	v_mov_b32_e32 v34, v28
	v_mov_b32_e32 v35, v31
	v_mov_b32_e32 v50, v24
	v_mov_b32_e32 v51, v27
	s_waitcnt vmcnt(13)
	v_mov_b32_e32 v52, v21
	v_mov_b32_e32 v53, v22
	v_mov_b32_e32 v54, v20
	v_mov_b32_e32 v55, v23
	s_waitcnt vmcnt(12)
	v_mov_b32_e32 v56, v17
	v_mov_b32_e32 v57, v18
	v_mov_b32_e32 v58, v16
	v_mov_b32_e32 v59, v19
	v_pk_add_f32 v[32:33], v[32:33], v[34:35]
	v_pk_add_f32 v[34:35], v[48:49], v[50:51]
	v_pk_add_f32 v[48:49], v[52:53], v[54:55]
	v_pk_add_f32 v[50:51], v[56:57], v[58:59]
	v_add_f32_e32 v45, v32, v33
	v_add_f32_e32 v47, v34, v35
	v_pk_add_f32 v[32:33], v[48:49], v[48:49] op_sel:[0,1] op_sel_hi:[1,0]
	v_pk_add_f32 v[34:35], v[50:51], v[50:51] op_sel:[0,1] op_sel_hi:[1,0]
	s_waitcnt vmcnt(11)
	v_add_f32_e32 v60, v12, v13
	v_add_f32_e32 v74, v14, v15
	s_waitcnt vmcnt(10)
	v_add_f32_e32 v76, v8, v9
	v_add_f32_e32 v78, v10, v11
	s_waitcnt vmcnt(9)
	v_mov_b32_e32 v81, v4
	v_mov_b32_e32 v61, v6
	v_mov_b32_e32 v75, v7
	s_waitcnt vmcnt(8)
	v_mov_b32_e32 v83, v0
	v_mov_b32_e32 v77, v2
	v_mov_b32_e32 v79, v3
	v_add_f32_e32 v80, 0, v45
	v_add_f32_e32 v82, 0, v47
	v_mov_b32_e32 v33, v5
	v_mov_b32_e32 v35, v1
	v_pk_add_f32 v[52:53], v[60:61], v[74:75]
	v_pk_add_f32 v[54:55], v[76:77], v[78:79]
	v_pk_add_f32 v[32:33], v[80:81], v[32:33]
	v_pk_add_f32 v[34:35], v[82:83], v[34:35]
	v_pk_add_f32 v[32:33], v[32:33], v[52:53]
	v_pk_add_f32 v[34:35], v[34:35], v[54:55]
	v_add_f32_e32 v32, v32, v33
	v_add_f32_e32 v33, v34, v35
	ds_bpermute_b32 v34, v62, v32
	ds_bpermute_b32 v35, v62, v33
	s_waitcnt lgkmcnt(1)
	v_add_f32_e32 v32, v32, v34
	s_waitcnt lgkmcnt(0)
	v_add_f32_e32 v33, v33, v35
	ds_bpermute_b32 v34, v63, v32
	ds_bpermute_b32 v35, v63, v33
	s_waitcnt lgkmcnt(1)
	v_add_f32_e32 v32, v32, v34
	s_waitcnt lgkmcnt(0)
	v_add_f32_e32 v33, v33, v35
	ds_bpermute_b32 v34, v64, v32
	ds_bpermute_b32 v35, v64, v33
	s_waitcnt lgkmcnt(1)
	v_add_f32_e32 v32, v32, v34
	s_waitcnt lgkmcnt(0)
	v_add_f32_e32 v33, v33, v35
	ds_bpermute_b32 v34, v65, v32
	ds_bpermute_b32 v35, v65, v33
	s_waitcnt lgkmcnt(1)
	v_add_f32_e32 v32, v32, v34
	s_waitcnt lgkmcnt(0)
	v_add_f32_e32 v33, v33, v35
	ds_bpermute_b32 v34, v66, v32
	ds_bpermute_b32 v35, v66, v33
	s_waitcnt lgkmcnt(1)
	v_add_f32_e32 v32, v32, v34
	s_waitcnt lgkmcnt(0)
	v_add_f32_e32 v33, v33, v35
	ds_bpermute_b32 v34, v67, v32
	ds_bpermute_b32 v35, v67, v33
	s_waitcnt lgkmcnt(1)
	v_add_f32_e32 v45, v32, v34
	s_waitcnt lgkmcnt(0)
	v_add_f32_e32 v47, v33, v35
	v_fmamk_f32 v57, v45, 0xba800000, v29
	v_fmamk_f32 v56, v45, 0xba800000, v28
	v_fmamk_f32 v31, v45, 0xba800000, v31
	v_fmac_f32_e32 v30, 0xba800000, v45
	v_fmamk_f32 v53, v47, 0xba800000, v27
	v_fmamk_f32 v52, v47, 0xba800000, v26
	v_fmamk_f32 v25, v47, 0xba800000, v25
	v_fmac_f32_e32 v24, 0xba800000, v47
	v_fmamk_f32 v55, v45, 0xba800000, v23
	v_fmamk_f32 v54, v45, 0xba800000, v22
	v_fmamk_f32 v51, v45, 0xba800000, v15
	v_fmamk_f32 v50, v45, 0xba800000, v14
	v_pk_mul_f32 v[14:15], v[30:31], v[30:31]
	v_pk_mul_f32 v[22:23], v[56:57], v[56:57]
	v_pk_mul_f32 v[26:27], v[52:53], v[52:53]
	v_pk_mul_f32 v[28:29], v[24:25], v[24:25]
	v_pk_mov_b32 v[60:61], v[22:23], v[14:15] op_sel:[1,0]
	v_mov_b32_e32 v23, v15
	v_pk_mov_b32 v[14:15], v[28:29], v[26:27] op_sel:[1,0]
	v_mov_b32_e32 v29, v27
	v_fmamk_f32 v21, v45, 0xba800000, v21
	v_fmac_f32_e32 v20, 0xba800000, v45
	v_fmamk_f32 v19, v47, 0xba800000, v19
	v_fmamk_f32 v18, v47, 0xba800000, v18
	v_fmamk_f32 v17, v47, 0xba800000, v17
	v_fmac_f32_e32 v16, 0xba800000, v47
	v_pk_add_f32 v[14:15], v[14:15], v[28:29]
	v_fmac_f32_e32 v12, 0xba800000, v45
	v_pk_mul_f32 v[32:33], v[54:55], v[54:55]
	v_pk_mul_f32 v[34:35], v[20:21], v[20:21]
	v_pk_mul_f32 v[48:49], v[18:19], v[18:19]
	v_pk_mul_f32 v[58:59], v[16:17], v[16:17]
	v_pk_add_f32 v[14:15], v[14:15], v[14:15] op_sel_hi:[0,1]
	v_fmamk_f32 v13, v45, 0xba800000, v13
	v_pk_mov_b32 v[26:27], v[34:35], v[32:33] op_sel:[1,0]
	v_mov_b32_e32 v35, v33
	v_pk_mov_b32 v[32:33], v[58:59], v[48:49] op_sel:[1,0]
	v_mov_b32_e32 v59, v49
	v_mul_f32_e32 v14, v12, v12
	v_pk_add_f32 v[22:23], v[22:23], v[60:61]
	v_pk_add_f32 v[26:27], v[34:35], v[26:27]
	v_pk_add_f32 v[28:29], v[32:33], v[58:59]
	v_pk_fma_f32 v[32:33], v[12:13], v[12:13], v[14:15] op_sel_hi:[1,1,0]
	v_mul_f32_e32 v14, v50, v50
	v_pk_add_f32 v[22:23], v[22:23], v[22:23] op_sel_hi:[0,1]
	v_pk_add_f32 v[26:27], v[26:27], v[26:27] op_sel_hi:[0,1]
	v_pk_fma_f32 v[34:35], v[50:51], v[50:51], v[14:15] op_sel_hi:[1,1,0]
	v_fmamk_f32 v49, v45, 0xba800000, v7
	v_fmamk_f32 v48, v45, 0xba800000, v6
	v_fmamk_f32 v5, v45, 0xba800000, v5
	v_fmac_f32_e32 v4, 0xba800000, v45
	v_mul_f32_e32 v32, v4, v4
	v_mul_f32_e32 v34, v5, v5
	v_mul_f32_e32 v26, v48, v48
	v_mul_f32_e32 v22, v49, v49
	v_pk_add_f32 v[6:7], v[32:33], v[34:35]
	v_pk_add_f32 v[22:23], v[22:23], v[26:27]
	v_fmac_f32_e32 v8, 0xba800000, v47
	v_pk_add_f32 v[6:7], v[6:7], v[22:23]
	v_fmamk_f32 v10, v47, 0xba800000, v10
	v_add_f32_e32 v22, v6, v7
	ds_bpermute_b32 v23, v62, v22
	v_fmamk_f32 v9, v47, 0xba800000, v9
	v_mul_f32_e32 v14, v8, v8
	v_fmamk_f32 v11, v47, 0xba800000, v11
	v_pk_add_f32 v[28:29], v[28:29], v[28:29] op_sel_hi:[0,1]
	v_pk_fma_f32 v[58:59], v[8:9], v[8:9], v[14:15] op_sel_hi:[1,1,0]
	v_mul_f32_e32 v14, v10, v10
	v_fmamk_f32 v3, v47, 0xba800000, v3
	v_fmamk_f32 v2, v47, 0xba800000, v2
	v_pk_fma_f32 v[60:61], v[10:11], v[10:11], v[14:15] op_sel_hi:[1,1,0]
	v_mul_f32_e32 v14, v2, v2
	v_mul_f32_e32 v28, v3, v3
	v_pk_add_f32 v[14:15], v[14:15], v[28:29]
	s_waitcnt lgkmcnt(0)
	v_add_f32_e32 v22, v22, v23
	ds_bpermute_b32 v23, v63, v22
	v_fmamk_f32 v1, v47, 0xba800000, v1
	v_fmac_f32_e32 v0, 0xba800000, v47
	v_mul_f32_e32 v58, v0, v0
	v_mul_f32_e32 v60, v1, v1
	v_pk_add_f32 v[6:7], v[58:59], v[60:61]
	v_ashrrev_i32_e32 v45, 31, v44
	v_pk_add_f32 v[6:7], v[6:7], v[14:15]
	s_waitcnt lgkmcnt(0)
	v_add_f32_e32 v14, v22, v23
	v_add_f32_e32 v6, v6, v7
	ds_bpermute_b32 v7, v62, v6
	ds_bpermute_b32 v15, v64, v14
	v_ashrrev_i32_e32 v47, 31, v46
	s_waitcnt lgkmcnt(1)
	v_add_f32_e32 v6, v6, v7
	s_waitcnt lgkmcnt(0)
	v_add_f32_e32 v14, v14, v15
	ds_bpermute_b32 v7, v63, v6
	ds_bpermute_b32 v15, v65, v14
	s_waitcnt lgkmcnt(1)
	v_add_f32_e32 v6, v6, v7
	s_waitcnt lgkmcnt(0)
	v_add_f32_e32 v14, v14, v15
	ds_bpermute_b32 v7, v64, v6
	ds_bpermute_b32 v15, v66, v14
	s_waitcnt lgkmcnt(1)
	v_add_f32_e32 v6, v6, v7
	s_waitcnt lgkmcnt(0)
	v_add_f32_e32 v14, v14, v15
	ds_bpermute_b32 v7, v65, v6
	ds_bpermute_b32 v15, v67, v14
	s_waitcnt lgkmcnt(1)
	v_add_f32_e32 v22, v6, v7
	s_waitcnt lgkmcnt(0)
	v_add_f32_e32 v6, v14, v15
	v_fmamk_f32 v6, v6, 0x3a800000, v71
	v_mul_f32_e32 v7, 0x4f800000, v6
	v_cmp_gt_f32_e32 vcc, s39, v6
	ds_bpermute_b32 v23, v66, v22
	s_waitcnt lgkmcnt(0)
	v_add_f32_e32 v22, v22, v23
	v_cndmask_b32_e32 v14, v6, v7, vcc
	v_sqrt_f32_e32 v15, v14
	v_lshlrev_b64 v[6:7], 11, v[44:45]
	ds_bpermute_b32 v23, v67, v22
	v_add_u32_e32 v44, -1, v15
	v_fma_f32 v45, -v44, v15, v14
	v_cmp_ge_f32_e64 s[0:1], 0, v45
	v_add_u32_e32 v45, 1, v15
	s_waitcnt lgkmcnt(0)
	v_add_f32_e32 v22, v22, v23
	v_cndmask_b32_e64 v44, v15, v44, s[0:1]
	v_fma_f32 v15, -v45, v15, v14
	v_cmp_lt_f32_e64 s[0:1], 0, v15
	v_fmamk_f32 v22, v22, 0x3a800000, v71
	s_nop 0
	v_cndmask_b32_e64 v15, v44, v45, s[0:1]
	v_mul_f32_e32 v44, 0x37800000, v15
	v_cndmask_b32_e32 v15, v15, v44, vcc
	v_cmp_class_f32_e32 vcc, v14, v72
	s_nop 1
	v_cndmask_b32_e32 v44, v15, v14, vcc
	v_div_scale_f32 v45, s[0:1], v44, v44, 1.0
	v_rcp_f32_e32 v58, v45
	v_lshlrev_b64 v[14:15], 11, v[46:47]
	v_mul_f32_e32 v47, 0x4f800000, v22
	v_cmp_gt_f32_e64 s[0:1], s39, v22
	v_fma_f32 v23, -v45, v58, 1.0
	v_fmac_f32_e32 v58, v23, v58
	v_cndmask_b32_e64 v22, v22, v47, s[0:1]
	v_div_scale_f32 v23, vcc, 1.0, v44, 1.0
	v_sqrt_f32_e32 v47, v22
	v_mul_f32_e32 v46, v23, v58
	v_fma_f32 v59, -v45, v46, v23
	v_fmac_f32_e32 v46, v59, v58
	v_fma_f32 v23, -v45, v46, v23
	v_add_u32_e32 v45, -1, v47
	v_fma_f32 v59, -v45, v47, v22
	v_cmp_ge_f32_e64 s[6:7], 0, v59
	v_add_u32_e32 v59, 1, v47
	v_div_fmas_f32 v23, v23, v58, v46
	v_cndmask_b32_e64 v45, v47, v45, s[6:7]
	v_fma_f32 v47, -v59, v47, v22
	v_cmp_lt_f32_e64 s[6:7], 0, v47
	v_div_fixup_f32 v60, v23, v44, 1.0
	s_nop 0
	v_cndmask_b32_e64 v45, v45, v59, s[6:7]
	v_mul_f32_e32 v47, 0x37800000, v45
	v_cndmask_b32_e64 v45, v45, v47, s[0:1]
	v_cmp_class_f32_e64 s[0:1], v22, v72
	v_lshl_add_u64 v[58:59], v[42:43], 0, v[6:7]
	v_pk_mul_f32 v[6:7], v[56:57], v[60:61] op_sel_hi:[1,0]
	v_cndmask_b32_e64 v22, v45, v22, s[0:1]
	v_div_scale_f32 v45, s[0:1], v22, v22, 1.0
	v_rcp_f32_e32 v47, v45
	v_pk_fma_f32 v[6:7], v[84:85], v[6:7], v[88:89]
	v_fma_f32 v23, -v45, v47, 1.0
	v_fmac_f32_e32 v47, v23, v47
	v_div_scale_f32 v23, vcc, 1.0, v22, 1.0
	v_mul_f32_e32 v44, v23, v47
	v_fma_f32 v46, -v45, v44, v23
	v_fmac_f32_e32 v44, v46, v47
	v_fma_f32 v23, -v45, v44, v23
	v_div_fmas_f32 v23, v23, v47, v44
	v_div_fixup_f32 v46, v23, v22, 1.0
	v_mov_b32_e32 v47, v46
	v_lshl_add_u64 v[44:45], v[42:43], 0, v[14:15]
	v_pk_mul_f32 v[14:15], v[30:31], v[60:61] op_sel_hi:[1,0]
	v_cvt_pk_bf16_f32 v6, v6, v7
	s_nop 0
	v_pk_fma_f32 v[14:15], v[86:87], v[14:15], v[90:91]
	s_nop 0
	v_cvt_pk_bf16_f32 v7, v14, v15
	global_store_dwordx2 v[58:59], v[6:7], off
	s_and_saveexec_b64 s[0:1], s[4:5]
	s_cbranch_execz .LBB0_122
	v_mov_b32_e32 v6, v46
	v_mov_b32_e32 v7, v46
	v_pk_mul_f32 v[14:15], v[24:25], v[46:47]
	v_pk_mul_f32 v[6:7], v[52:53], v[6:7]
	v_pk_fma_f32 v[14:15], v[84:85], v[14:15], v[88:89]
	v_pk_fma_f32 v[6:7], v[86:87], v[6:7], v[90:91]
	v_cvt_pk_bf16_f32 v14, v14, v15
	s_nop 0
	v_cvt_pk_bf16_f32 v15, v6, v7
	global_store_dwordx2 v[44:45], v[14:15], off
.LBB0_122:
	s_or_b64 exec, exec, s[0:1]
	v_mov_b32_e32 v61, v60
	v_mov_b32_e32 v6, v60
	v_mov_b32_e32 v7, v60
	v_pk_mul_f32 v[20:21], v[20:21], v[60:61]
	v_pk_mul_f32 v[14:15], v[54:55], v[6:7]
	v_pk_fma_f32 v[20:21], v[20:21], v[92:93], v[96:97]
	v_pk_fma_f32 v[14:15], v[14:15], v[94:95], v[98:99]
	v_cvt_pk_bf16_f32 v20, v20, v21
	s_nop 0
	v_cvt_pk_bf16_f32 v21, v14, v15
	global_store_dwordx2 v[58:59], v[20:21], off offset:512
	s_and_saveexec_b64 s[0:1], s[4:5]
	s_cbranch_execz .LBB0_124
	v_mov_b32_e32 v14, v46
	v_mov_b32_e32 v15, v46
	v_pk_mul_f32 v[16:17], v[16:17], v[46:47]
	v_pk_mul_f32 v[14:15], v[18:19], v[14:15]
	v_pk_fma_f32 v[16:17], v[16:17], v[92:93], v[96:97]
	v_pk_fma_f32 v[14:15], v[14:15], v[94:95], v[98:99]
	v_cvt_pk_bf16_f32 v16, v16, v17
	s_nop 0
	v_cvt_pk_bf16_f32 v17, v14, v15
	global_store_dwordx2 v[44:45], v[16:17], off offset:512
.LBB0_124:
	s_or_b64 exec, exec, s[0:1]
	v_pk_mul_f32 v[12:13], v[12:13], v[60:61]
	v_pk_mul_f32 v[6:7], v[50:51], v[6:7]
	v_pk_fma_f32 v[12:13], v[12:13], v[100:101], v[104:105]
	v_pk_fma_f32 v[6:7], v[6:7], v[102:103], v[106:107]
	v_cvt_pk_bf16_f32 v12, v12, v13
	s_nop 0
	v_cvt_pk_bf16_f32 v13, v6, v7
	global_store_dwordx2 v[58:59], v[12:13], off offset:1024
	s_and_saveexec_b64 s[0:1], s[4:5]
	s_cbranch_execz .LBB0_126
	v_mov_b32_e32 v6, v46
	v_mov_b32_e32 v7, v46
	v_pk_mul_f32 v[8:9], v[8:9], v[46:47]
	v_pk_mul_f32 v[6:7], v[10:11], v[6:7]
	v_pk_fma_f32 v[8:9], v[8:9], v[100:101], v[104:105]
	v_pk_fma_f32 v[6:7], v[6:7], v[102:103], v[106:107]
	v_cvt_pk_bf16_f32 v8, v8, v9
	s_nop 0
	v_cvt_pk_bf16_f32 v9, v6, v7
	global_store_dwordx2 v[44:45], v[8:9], off offset:1024
.LBB0_126:
	s_or_b64 exec, exec, s[0:1]
	v_mov_b32_e32 v14, v60
	v_mov_b32_e32 v15, v60
	v_pk_mul_f32 v[4:5], v[4:5], v[60:61]
	v_pk_mul_f32 v[14:15], v[48:49], v[14:15]
	v_pk_fma_f32 v[4:5], v[4:5], v[108:109], v[112:113]
	v_pk_fma_f32 v[14:15], v[14:15], v[110:111], v[114:115]
	v_cvt_pk_bf16_f32 v4, v4, v5
	s_nop 0
	v_cvt_pk_bf16_f32 v5, v14, v15
	global_store_dwordx2 v[58:59], v[4:5], off offset:1536
	s_and_saveexec_b64 s[0:1], s[4:5]
	s_cbranch_execz .LBB0_103
	v_mov_b32_e32 v4, v46
	v_mov_b32_e32 v5, v46
	v_pk_mul_f32 v[0:1], v[0:1], v[46:47]
	v_pk_mul_f32 v[2:3], v[2:3], v[4:5]
	v_pk_fma_f32 v[0:1], v[0:1], v[108:109], v[112:113]
	v_pk_fma_f32 v[2:3], v[2:3], v[110:111], v[114:115]
	v_cvt_pk_bf16_f32 v0, v0, v1
	s_nop 0
	v_cvt_pk_bf16_f32 v1, v2, v3
	global_store_dwordx2 v[44:45], v[0:1], off offset:1536
	s_branch .LBB0_103

.LBB0_860:
	s_or_b64 exec, exec, s[0:1]
	s_waitcnt lgkmcnt(0)
	v_lshlrev_b32_e32 v0, 3, v224
	v_mov_b32_e32 v17, 0
	v_lshlrev_b32_e32 v16, 4, v224
	v_add_u32_e32 v188, s15, v218
	s_movk_i32 s2, 0x4000
	v_lshl_add_u64 v[176:177], s[56:57], 0, v[16:17]
	v_lshlrev_b32_e32 v178, 2, v0
	s_barrier
	v_cmp_gt_i32_e64 s[0:1], s2, v188
	s_mov_b64 s[24:25], exec
	s_nop 0
	v_writelane_b32 v250, s0, 45
	s_nop 1
	v_writelane_b32 v250, s1, 46
	s_and_b64 s[0:1], s[24:25], s[0:1]
	s_mov_b64 exec, s[0:1]
	s_cbranch_execz .LBB0_867
	v_mbcnt_hi_u32_b32 v1, -1, v225
	v_and_b32_e32 v2, 64, v1
	v_add_u32_e32 v2, 64, v2
	v_xor_b32_e32 v3, 1, v1
	v_cmp_lt_i32_e32 vcc, v3, v2
	v_mov_b32_e32 v179, v17
	v_lshlrev_b32_e32 v16, 1, v0
	v_cndmask_b32_e32 v3, v1, v3, vcc
	v_lshlrev_b32_e32 v28, 2, v3
	v_xor_b32_e32 v3, 2, v1
	v_cmp_lt_i32_e32 vcc, v3, v2
	v_lshl_add_u64 v[18:19], s[22:23], 0, v[178:179]
	v_lshl_add_u64 v[20:21], s[68:69], 0, v[178:179]
	v_cndmask_b32_e32 v3, v1, v3, vcc
	v_lshlrev_b32_e32 v29, 2, v3
	v_xor_b32_e32 v3, 4, v1
	v_cmp_lt_i32_e32 vcc, v3, v2
	v_lshl_add_u64 v[22:23], s[36:37], 0, v[16:17]
	s_mov_b64 s[26:27], 0
	v_cndmask_b32_e32 v3, v1, v3, vcc
	v_lshlrev_b32_e32 v30, 2, v3
	v_xor_b32_e32 v3, 8, v1
	v_cmp_lt_i32_e32 vcc, v3, v2
	v_mov_b32_e32 v34, 0x3727c5ac
	s_mov_b32 s3, 0xf800000
	v_cndmask_b32_e32 v3, v1, v3, vcc
	v_lshlrev_b32_e32 v31, 2, v3
	v_xor_b32_e32 v3, 16, v1
	v_cmp_lt_i32_e32 vcc, v3, v2
	v_mov_b32_e32 v35, 0x260
	v_mov_b32_e32 v0, v188
	v_cndmask_b32_e32 v3, v1, v3, vcc
	v_lshlrev_b32_e32 v32, 2, v3
	v_xor_b32_e32 v3, 32, v1
	v_cmp_lt_i32_e32 vcc, v3, v2
	s_nop 1
	v_cndmask_b32_e32 v1, v1, v3, vcc
	v_lshlrev_b32_e32 v33, 2, v1
	global_load_dwordx4 v[76:79], v[18:19], off offset:16
	global_load_dwordx4 v[80:83], v[18:19], off
	global_load_dwordx4 v[84:87], v[20:21], off offset:16
	global_load_dwordx4 v[88:91], v[20:21], off
	global_load_dwordx4 v[92:95], v[18:19], off offset:2064
	global_load_dwordx4 v[96:99], v[18:19], off offset:2048
	global_load_dwordx4 v[100:103], v[20:21], off offset:2048
	global_load_dwordx4 v[104:107], v[20:21], off offset:2064
	s_waitcnt vmcnt(0)
	s_branch .LBB0_863

.LBB0_863:
	v_add_u32_e32 v36, s64, v0
	v_cmp_gt_i32_e64 s[40:41], s2, v36
	v_ashrrev_i32_e32 v1, 31, v0
	v_lshlrev_b64 v[26:27], 11, v[0:1]
	v_cndmask_b32_e64 v2, v0, v36, s[40:41]
	v_ashrrev_i32_e32 v3, 31, v2
	v_lshlrev_b64 v[2:3], 11, v[2:3]
	v_lshl_add_u64 v[8:9], v[176:177], 0, v[26:27]
	v_lshl_add_u64 v[12:13], v[176:177], 0, v[2:3]
	s_lshl_b32 s34, s64, 12
	s_mov_b32 s35, 0
	v_lshl_add_u64 v[108:109], v[8:9], 0, s[34:35]
	v_lshl_add_u64 v[110:111], v[12:13], 0, s[34:35]
	v_lshl_add_u64 v[24:25], s[36:37], 0, v[2:3]
	global_load_dwordx4 v[0:3], v[8:9], off
	global_load_dwordx4 v[4:7], v[12:13], off
	s_nop 0
	global_load_dwordx4 v[8:11], v[8:9], off offset:1024
	s_nop 0
	global_load_dwordx4 v[12:15], v[12:13], off offset:1024
	global_load_dwordx4 v[112:115], v[108:109], off
	global_load_dwordx4 v[112:115], v[110:111], off
	global_load_dwordx4 v[112:115], v[108:109], off offset:1024
	global_load_dwordx4 v[112:115], v[110:111], off offset:1024
	v_lshl_add_u64 v[26:27], v[22:23], 0, v[26:27]
	s_waitcnt vmcnt(7)
	v_lshlrev_b32_e32 v67, 16, v0
	v_and_b32_e32 v65, 0xffff0000, v0
	v_add_f32_e32 v0, 0, v67
	v_lshlrev_b32_e32 v63, 16, v1
	v_add_f32_e32 v0, v0, v65
	v_and_b32_e32 v61, 0xffff0000, v1
	v_add_f32_e32 v0, v0, v63
	v_lshlrev_b32_e32 v68, 16, v2
	v_add_f32_e32 v0, v0, v61
	v_and_b32_e32 v66, 0xffff0000, v2
	s_waitcnt vmcnt(6)
	v_lshlrev_b32_e32 v45, 16, v4
	v_add_f32_e32 v0, v0, v68
	v_lshlrev_b32_e32 v64, 16, v3
	v_and_b32_e32 v46, 0xffff0000, v4
	v_add_f32_e32 v1, 0, v45
	v_add_f32_e32 v0, v0, v66
	v_and_b32_e32 v62, 0xffff0000, v3
	v_lshlrev_b32_e32 v49, 16, v5
	v_add_f32_e32 v1, v1, v46
	v_add_f32_e32 v0, v0, v64
	v_and_b32_e32 v55, 0xffff0000, v5
	s_waitcnt vmcnt(5)
	v_lshlrev_b32_e32 v58, 16, v8
	v_add_f32_e32 v1, v1, v49
	v_add_f32_e32 v0, v0, v62
	v_lshlrev_b32_e32 v47, 16, v6
	v_and_b32_e32 v54, 0xffff0000, v8
	v_add_f32_e32 v1, v1, v55
	v_add_f32_e32 v0, v0, v58
	v_and_b32_e32 v51, 0xffff0000, v6
	v_lshlrev_b32_e32 v52, 16, v9
	v_add_f32_e32 v1, v1, v47
	v_add_f32_e32 v0, v0, v54
	v_lshlrev_b32_e32 v56, 16, v7
	v_and_b32_e32 v48, 0xffff0000, v9
	v_add_f32_e32 v1, v1, v51
	v_add_f32_e32 v0, v0, v52
	v_and_b32_e32 v60, 0xffff0000, v7
	v_lshlrev_b32_e32 v59, 16, v10
	v_add_f32_e32 v1, v1, v56
	v_add_f32_e32 v0, v0, v48
	v_and_b32_e32 v57, 0xffff0000, v10
	s_waitcnt vmcnt(4)
	v_lshlrev_b32_e32 v37, 16, v12
	v_add_f32_e32 v1, v1, v60
	v_add_f32_e32 v0, v0, v59
	v_lshlrev_b32_e32 v53, 16, v11
	v_and_b32_e32 v38, 0xffff0000, v12
	v_add_f32_e32 v1, v1, v37
	v_add_f32_e32 v0, v0, v57
	v_and_b32_e32 v50, 0xffff0000, v11
	v_lshlrev_b32_e32 v40, 16, v13
	v_add_f32_e32 v1, v1, v38
	v_add_f32_e32 v0, v0, v53
	v_and_b32_e32 v42, 0xffff0000, v13
	v_add_f32_e32 v1, v1, v40
	v_add_f32_e32 v0, v0, v50
	v_lshlrev_b32_e32 v39, 16, v14
	v_add_f32_e32 v1, v1, v42
	ds_bpermute_b32 v2, v28, v0
	v_and_b32_e32 v41, 0xffff0000, v14
	v_add_f32_e32 v1, v1, v39
	v_lshlrev_b32_e32 v43, 16, v15
	v_add_f32_e32 v1, v1, v41
	v_and_b32_e32 v44, 0xffff0000, v15
	v_add_f32_e32 v1, v1, v43
	v_add_f32_e32 v1, v1, v44
	s_waitcnt lgkmcnt(0)
	v_add_f32_e32 v0, v0, v2
	ds_bpermute_b32 v2, v28, v1
	s_waitcnt lgkmcnt(0)
	v_add_f32_e32 v1, v1, v2
	ds_bpermute_b32 v2, v29, v0
	s_waitcnt lgkmcnt(0)
	v_add_f32_e32 v0, v0, v2
	ds_bpermute_b32 v2, v29, v1
	s_waitcnt lgkmcnt(0)
	v_add_f32_e32 v1, v1, v2
	ds_bpermute_b32 v2, v30, v0
	s_waitcnt lgkmcnt(0)
	v_add_f32_e32 v0, v0, v2
	ds_bpermute_b32 v2, v30, v1
	s_waitcnt lgkmcnt(0)
	v_add_f32_e32 v1, v1, v2
	ds_bpermute_b32 v2, v31, v0
	s_waitcnt lgkmcnt(0)
	v_add_f32_e32 v0, v0, v2
	ds_bpermute_b32 v2, v31, v1
	s_waitcnt lgkmcnt(0)
	v_add_f32_e32 v1, v1, v2
	ds_bpermute_b32 v2, v32, v0
	s_waitcnt lgkmcnt(0)
	v_add_f32_e32 v0, v0, v2
	ds_bpermute_b32 v2, v32, v1
	s_waitcnt lgkmcnt(0)
	v_add_f32_e32 v1, v1, v2
	ds_bpermute_b32 v2, v33, v0
	s_waitcnt lgkmcnt(0)
	v_add_f32_e32 v0, v0, v2
	ds_bpermute_b32 v2, v33, v1
	v_fmac_f32_e32 v65, 0xba800000, v0
	v_fmac_f32_e32 v67, 0xba800000, v0
	v_fmac_f32_e32 v63, 0xba800000, v0
	v_fmac_f32_e32 v61, 0xba800000, v0
	s_waitcnt lgkmcnt(0)
	v_add_f32_e32 v1, v1, v2
	v_mul_f32_e32 v2, v65, v65
	v_fmac_f32_e32 v2, v67, v67
	v_fmac_f32_e32 v2, v63, v63
	v_fmac_f32_e32 v2, v61, v61
	v_fmac_f32_e32 v68, 0xba800000, v0
	v_fmac_f32_e32 v46, 0xba800000, v1
	v_fmac_f32_e32 v2, v68, v68
	v_fmac_f32_e32 v66, 0xba800000, v0
	v_fmac_f32_e32 v45, 0xba800000, v1
	v_mul_f32_e32 v3, v46, v46
	v_fmac_f32_e32 v2, v66, v66
	v_fmac_f32_e32 v64, 0xba800000, v0
	v_fmac_f32_e32 v3, v45, v45
	v_fmac_f32_e32 v49, 0xba800000, v1
	v_fmac_f32_e32 v2, v64, v64
	v_fmac_f32_e32 v62, 0xba800000, v0
	v_fmac_f32_e32 v3, v49, v49
	v_fmac_f32_e32 v55, 0xba800000, v1
	v_fmac_f32_e32 v2, v62, v62
	v_fmac_f32_e32 v58, 0xba800000, v0
	v_fmac_f32_e32 v3, v55, v55
	v_fmac_f32_e32 v47, 0xba800000, v1
	v_fmac_f32_e32 v2, v58, v58
	v_fmac_f32_e32 v54, 0xba800000, v0
	v_fmac_f32_e32 v3, v47, v47
	v_fmac_f32_e32 v51, 0xba800000, v1
	v_fmac_f32_e32 v2, v54, v54
	v_fmac_f32_e32 v52, 0xba800000, v0
	v_fmac_f32_e32 v3, v51, v51
	v_fmac_f32_e32 v56, 0xba800000, v1
	v_fmac_f32_e32 v2, v52, v52
	v_fmac_f32_e32 v48, 0xba800000, v0
	v_fmac_f32_e32 v3, v56, v56
	v_fmac_f32_e32 v60, 0xba800000, v1
	v_fmac_f32_e32 v2, v48, v48
	v_fmac_f32_e32 v59, 0xba800000, v0
	v_fmac_f32_e32 v3, v60, v60
	v_fmac_f32_e32 v37, 0xba800000, v1
	v_fmac_f32_e32 v2, v59, v59
	v_fmac_f32_e32 v57, 0xba800000, v0
	v_fmac_f32_e32 v3, v37, v37
	v_fmac_f32_e32 v38, 0xba800000, v1
	v_fmac_f32_e32 v2, v57, v57
	v_fmac_f32_e32 v53, 0xba800000, v0
	v_fmac_f32_e32 v3, v38, v38
	v_fmac_f32_e32 v40, 0xba800000, v1
	v_fmac_f32_e32 v2, v53, v53
	v_fmac_f32_e32 v50, 0xba800000, v0
	v_fmac_f32_e32 v3, v40, v40
	v_fmac_f32_e32 v42, 0xba800000, v1
	v_fmac_f32_e32 v2, v50, v50
	v_fmac_f32_e32 v3, v42, v42
	v_fmac_f32_e32 v39, 0xba800000, v1
	ds_bpermute_b32 v0, v28, v2
	v_fmac_f32_e32 v3, v39, v39
	v_fmac_f32_e32 v41, 0xba800000, v1
	v_fmac_f32_e32 v3, v41, v41
	v_fmac_f32_e32 v43, 0xba800000, v1
	v_fmac_f32_e32 v3, v43, v43
	v_fmac_f32_e32 v44, 0xba800000, v1
	v_fmac_f32_e32 v3, v44, v44
	s_waitcnt lgkmcnt(0)
	v_add_f32_e32 v0, v2, v0
	ds_bpermute_b32 v1, v28, v3
	ds_bpermute_b32 v2, v29, v0
	s_waitcnt lgkmcnt(1)
	v_add_f32_e32 v1, v3, v1
	s_waitcnt lgkmcnt(0)
	v_add_f32_e32 v0, v0, v2
	ds_bpermute_b32 v2, v29, v1
	s_waitcnt lgkmcnt(0)
	v_add_f32_e32 v1, v1, v2
	ds_bpermute_b32 v2, v30, v0
	s_waitcnt lgkmcnt(0)
	v_add_f32_e32 v0, v0, v2
	ds_bpermute_b32 v2, v30, v1
	s_waitcnt lgkmcnt(0)
	v_add_f32_e32 v1, v1, v2
	ds_bpermute_b32 v2, v31, v0
	s_waitcnt lgkmcnt(0)
	v_add_f32_e32 v0, v0, v2
	ds_bpermute_b32 v2, v31, v1
	s_waitcnt lgkmcnt(0)
	v_add_f32_e32 v1, v1, v2
	ds_bpermute_b32 v2, v32, v0
	s_waitcnt lgkmcnt(0)
	v_add_f32_e32 v0, v0, v2
	ds_bpermute_b32 v2, v32, v1
	s_waitcnt lgkmcnt(0)
	v_add_f32_e32 v1, v1, v2
	ds_bpermute_b32 v2, v33, v0
	s_waitcnt lgkmcnt(0)
	v_add_f32_e32 v0, v0, v2
	ds_bpermute_b32 v2, v33, v1
	v_fmamk_f32 v0, v0, 0x3a800000, v34
	v_cmp_gt_f32_e32 vcc, s3, v0
	s_waitcnt lgkmcnt(0)
	v_add_f32_e32 v1, v1, v2
	v_mul_f32_e32 v2, 0x4f800000, v0
	v_cndmask_b32_e32 v0, v0, v2, vcc
	v_sqrt_f32_e32 v2, v0
	s_nop 0
	v_add_u32_e32 v3, -1, v2
	v_fma_f32 v4, -v3, v2, v0
	v_cmp_ge_f32_e64 s[0:1], 0, v4
	v_add_u32_e32 v4, 1, v2
	s_nop 0
	v_cndmask_b32_e64 v3, v2, v3, s[0:1]
	v_fma_f32 v2, -v4, v2, v0
	v_cmp_lt_f32_e64 s[0:1], 0, v2
	s_nop 1
	v_cndmask_b32_e64 v2, v3, v4, s[0:1]
	v_mul_f32_e32 v3, 0x37800000, v2
	v_cndmask_b32_e32 v2, v2, v3, vcc
	v_cmp_class_f32_e32 vcc, v0, v35
	s_nop 1
	v_cndmask_b32_e32 v0, v2, v0, vcc
	v_div_scale_f32 v2, s[0:1], v0, v0, 1.0
	v_rcp_f32_e32 v3, v2
	s_nop 0
	v_fma_f32 v4, -v2, v3, 1.0
	v_fmac_f32_e32 v3, v4, v3
	v_div_scale_f32 v4, vcc, 1.0, v0, 1.0
	v_mul_f32_e32 v5, v4, v3
	v_fma_f32 v6, -v2, v5, v4
	v_fmac_f32_e32 v5, v6, v3
	v_fma_f32 v2, -v2, v5, v4
	v_div_fmas_f32 v2, v2, v3, v5
	v_div_fixup_f32 v70, v2, v0, 1.0
	v_fmamk_f32 v0, v1, 0x3a800000, v34
	v_cmp_gt_f32_e32 vcc, s3, v0
	v_mul_f32_e32 v1, 0x4f800000, v0
	v_mul_f32_e32 v65, v65, v70
	v_cndmask_b32_e32 v0, v0, v1, vcc
	v_sqrt_f32_e32 v1, v0
	v_mul_f32_e32 v63, v63, v70
	v_mul_f32_e32 v67, v67, v70
	v_mul_f32_e32 v68, v68, v70
	v_add_u32_e32 v2, -1, v1
	v_fma_f32 v3, -v2, v1, v0
	v_cmp_ge_f32_e64 s[0:1], 0, v3
	v_add_u32_e32 v3, 1, v1
	v_mul_f32_e32 v66, v66, v70
	v_cndmask_b32_e64 v2, v1, v2, s[0:1]
	v_fma_f32 v1, -v3, v1, v0
	v_cmp_lt_f32_e64 s[0:1], 0, v1
	v_mul_f32_e32 v64, v64, v70
	v_mul_f32_e32 v61, v61, v70
	v_cndmask_b32_e64 v1, v2, v3, s[0:1]
	v_mul_f32_e32 v2, 0x37800000, v1
	v_cndmask_b32_e32 v1, v1, v2, vcc
	v_cmp_class_f32_e32 vcc, v0, v35
	v_mul_f32_e32 v62, v62, v70
	s_nop 0
	v_cndmask_b32_e32 v0, v1, v0, vcc
	v_div_scale_f32 v1, s[0:1], v0, v0, 1.0
	v_rcp_f32_e32 v2, v1
	s_nop 0
	v_fma_f32 v3, -v1, v2, 1.0
	v_fmac_f32_e32 v2, v3, v2
	v_div_scale_f32 v3, vcc, 1.0, v0, 1.0
	v_mul_f32_e32 v4, v3, v2
	v_fma_f32 v5, -v1, v4, v3
	v_fmac_f32_e32 v4, v5, v2
	v_fma_f32 v1, -v1, v4, v3
	v_div_fmas_f32 v1, v1, v2, v4
	v_div_fixup_f32 v69, v1, v0, 1.0
	v_fma_f32 v68, v76, v68, v84
	v_fma_f32 v65, v81, v65, v89
	v_fma_f32 v63, v82, v63, v90
	v_fma_f32 v67, v80, v67, v88
	v_fma_f32 v66, v77, v66, v85
	v_fma_f32 v71, v78, v64, v86
	v_fma_f32 v61, v83, v61, v91
	v_fma_f32 v72, v79, v62, v87
	v_cvt_pk_bf16_f32 v62, v67, v65
	v_cvt_pk_bf16_f32 v63, v63, v61
	v_cvt_pk_bf16_f32 v64, v68, v66
	v_cvt_pk_bf16_f32 v65, v71, v72
	global_store_dwordx4 v[26:27], v[62:65], off
	s_and_saveexec_b64 s[0:1], s[40:41]
	s_cbranch_execz .LBB0_865
	v_mul_f32_e32 v60, v60, v69
	v_fma_f32 v3, v79, v60, v87
	v_mul_f32_e32 v7, v55, v69
	v_fma_f32 v7, v83, v7, v91
	v_mul_f32_e32 v11, v56, v69
	v_fma_f32 v6, v78, v11, v86
	v_mul_f32_e32 v2, v49, v69
	v_fma_f32 v2, v82, v2, v90
	v_mul_f32_e32 v10, v51, v69
	v_fma_f32 v5, v77, v10, v85
	v_mul_f32_e32 v1, v46, v69
	v_fma_f32 v1, v81, v1, v89
	v_mul_f32_e32 v9, v47, v69
	v_fma_f32 v4, v76, v9, v84
	v_mul_f32_e32 v0, v45, v69
	v_fma_f32 v12, v80, v0, v88
	v_cvt_pk_bf16_f32 v0, v12, v1
	v_cvt_pk_bf16_f32 v1, v2, v7
	v_cvt_pk_bf16_f32 v2, v4, v5
	v_lshl_add_u64 v[4:5], v[24:25], 0, v[16:17]
	v_cvt_pk_bf16_f32 v3, v6, v3
	global_store_dwordx4 v[4:5], v[0:3], off
.LBB0_865:
	s_or_b64 exec, exec, s[0:1]
	v_mul_f32_e32 v46, v59, v70
	v_mul_f32_e32 v47, v54, v70
	v_mul_f32_e32 v49, v57, v70
	v_mul_f32_e32 v51, v52, v70
	v_mul_f32_e32 v48, v48, v70
	v_mul_f32_e32 v45, v58, v70
	v_mul_f32_e32 v52, v53, v70
	v_mul_f32_e32 v50, v50, v70
	v_fma_f32 v48, v48, v99, v103
	v_fma_f32 v53, v46, v92, v104
	v_fma_f32 v46, v47, v97, v101
	v_fma_f32 v49, v49, v93, v105
	v_fma_f32 v47, v51, v98, v102
	v_fma_f32 v45, v45, v96, v100
	v_fma_f32 v51, v52, v94, v106
	v_fma_f32 v50, v50, v95, v107
	v_cvt_pk_bf16_f32 v46, v45, v46
	v_cvt_pk_bf16_f32 v47, v47, v48
	v_cvt_pk_bf16_f32 v48, v53, v49
	v_cvt_pk_bf16_f32 v49, v51, v50
	global_store_dwordx4 v[26:27], v[46:49], off offset:1024
	s_and_saveexec_b64 s[0:1], s[40:41]
	s_cbranch_execz .LBB0_862
	v_mul_f32_e32 v26, v44, v69
	v_fma_f32 v7, v26, v95, v107
	v_mul_f32_e32 v15, v42, v69
	v_fma_f32 v3, v15, v99, v103
	v_mul_f32_e32 v11, v43, v69
	v_fma_f32 v6, v11, v94, v106
	v_mul_f32_e32 v11, v40, v69
	v_fma_f32 v2, v11, v98, v102
	v_mul_f32_e32 v10, v41, v69
	v_fma_f32 v5, v10, v93, v105
	v_mul_f32_e32 v10, v38, v69
	v_fma_f32 v1, v10, v97, v101
	v_mul_f32_e32 v9, v39, v69
	v_fma_f32 v4, v9, v92, v104
	v_mul_f32_e32 v9, v37, v69
	v_fma_f32 v8, v9, v96, v100
	v_cvt_pk_bf16_f32 v0, v8, v1
	v_cvt_pk_bf16_f32 v1, v2, v3
	v_cvt_pk_bf16_f32 v2, v4, v5
	v_lshl_add_u64 v[4:5], v[24:25], 0, v[16:17]
	v_cvt_pk_bf16_f32 v3, v6, v7
	global_store_dwordx4 v[4:5], v[0:3], off offset:1024
	s_branch .LBB0_862
